# EpiZ per-head norm sums: lane^32 butterfly halves via copies + v_permlane32_swap instead of ds_bpermute with rebuilt addresses
# speedup vs baseline: 1.0034x; 1.0034x over previous
.LBB0_965:
	v_pk_mul_f32 v[98:99], v[110:111], v[110:111]
	v_pk_mul_f32 v[100:101], v[116:117], v[116:117]
	v_add_f32_e32 v98, v99, v98
	v_add_f32_e32 v98, v100, v98
	v_pk_mul_f32 v[136:137], v[112:113], v[112:113]
	v_add_f32_e32 v98, v101, v98
	v_add_f32_e32 v98, v136, v98
	v_pk_mul_f32 v[138:139], v[132:133], v[132:133]
	v_add_f32_e32 v98, v137, v98
	v_add_f32_e32 v98, v138, v98
	v_add_f32_e32 v98, v139, v98
	v_mov_b32_e32 v99, v98
	s_nop 1
	v_permlane16_swap_b32_e32 v99, v98
	v_pk_mul_f32 v[100:101], v[102:103], v[102:103]
	v_pk_mul_f32 v[136:137], v[106:107], v[106:107]
	v_pk_mul_f32 v[138:139], v[104:105], v[104:105]
	v_pk_mul_f32 v[140:141], v[108:109], v[108:109]
	s_waitcnt lgkmcnt(0)
	v_add_f32_e32 v98, v98, v99
	s_mov_b64 s[42:43], -1
	v_mov_b32_e32 v99, v98
	v_mov_b32_e32 v252, v98
	s_nop 1
	v_permlane32_swap_b32_e32 v99, v252
	s_and_b64 vcc, exec, s[10:11]
	s_waitcnt lgkmcnt(0)
	v_add_f32_e32 v99, v99, v252
	v_add_f32_e32 v98, v101, v100
	v_add_f32_e32 v98, v136, v98
	v_add_f32_e32 v98, v137, v98
	v_add_f32_e32 v98, v138, v98
	v_add_f32_e32 v98, v139, v98
	v_add_f32_e32 v98, v140, v98
	v_add_f32_e32 v98, v141, v98
	v_mov_b32_e32 v100, v98
	s_nop 1
	v_permlane16_swap_b32_e32 v100, v98
	s_waitcnt lgkmcnt(0)
	v_add_f32_e32 v98, v98, v100
	s_nop 0
	v_mov_b32_e32 v100, v98
	v_mov_b32_e32 v252, v98
	s_nop 1
	v_permlane32_swap_b32_e32 v100, v252
	s_waitcnt lgkmcnt(0)
	v_add_f32_e32 v101, v100, v252
	s_cbranch_vccnz .LBB0_967
	v_add_f32_e32 v98, v99, v101
	v_fmamk_f32 v98, v98, 0x3c800000, v228
	v_rsq_f32_e32 v98, v98
	s_mov_b64 s[42:43], 0

.LBB0_991:
	v_pk_mul_f32 v[82:83], v[94:95], v[94:95]
	v_pk_mul_f32 v[84:85], v[100:101], v[100:101]
	v_add_f32_e32 v82, v83, v82
	v_add_f32_e32 v82, v84, v82
	v_pk_mul_f32 v[104:105], v[96:97], v[96:97]
	v_add_f32_e32 v82, v85, v82
	v_add_f32_e32 v82, v104, v82
	v_pk_mul_f32 v[106:107], v[102:103], v[102:103]
	v_add_f32_e32 v82, v105, v82
	v_add_f32_e32 v82, v106, v82
	v_add_f32_e32 v82, v107, v82
	v_mov_b32_e32 v83, v82
	s_nop 1
	v_permlane16_swap_b32_e32 v83, v82
	v_pk_mul_f32 v[84:85], v[86:87], v[86:87]
	v_pk_mul_f32 v[104:105], v[90:91], v[90:91]
	v_pk_mul_f32 v[106:107], v[88:89], v[88:89]
	v_pk_mul_f32 v[108:109], v[92:93], v[92:93]
	s_waitcnt lgkmcnt(0)
	v_add_f32_e32 v82, v82, v83
	s_mov_b64 s[42:43], -1
	v_mov_b32_e32 v83, v82
	v_mov_b32_e32 v252, v82
	s_nop 1
	v_permlane32_swap_b32_e32 v83, v252
	s_and_b64 vcc, exec, s[10:11]
	s_waitcnt lgkmcnt(0)
	v_add_f32_e32 v83, v83, v252
	v_add_f32_e32 v82, v85, v84
	v_add_f32_e32 v82, v104, v82
	v_add_f32_e32 v82, v105, v82
	v_add_f32_e32 v82, v106, v82
	v_add_f32_e32 v82, v107, v82
	v_add_f32_e32 v82, v108, v82
	v_add_f32_e32 v82, v109, v82
	v_mov_b32_e32 v84, v82
	s_nop 1
	v_permlane16_swap_b32_e32 v84, v82
	s_waitcnt lgkmcnt(0)
	v_add_f32_e32 v82, v82, v84
	s_nop 0
	v_mov_b32_e32 v84, v82
	v_mov_b32_e32 v252, v82
	s_nop 1
	v_permlane32_swap_b32_e32 v84, v252
	s_waitcnt lgkmcnt(0)
	v_add_f32_e32 v85, v84, v252
	s_cbranch_vccnz .LBB0_993
	v_add_f32_e32 v82, v83, v85
	v_fmamk_f32 v82, v82, 0x3c800000, v228
	v_rsq_f32_e32 v82, v82
	s_mov_b64 s[42:43], 0

.LBB0_1017:
	v_pk_mul_f32 v[66:67], v[78:79], v[78:79]
	v_pk_mul_f32 v[68:69], v[84:85], v[84:85]
	v_add_f32_e32 v66, v67, v66
	v_add_f32_e32 v66, v68, v66
	v_pk_mul_f32 v[88:89], v[80:81], v[80:81]
	v_add_f32_e32 v66, v69, v66
	v_add_f32_e32 v66, v88, v66
	v_pk_mul_f32 v[90:91], v[86:87], v[86:87]
	v_add_f32_e32 v66, v89, v66
	v_add_f32_e32 v66, v90, v66
	v_add_f32_e32 v66, v91, v66
	v_mov_b32_e32 v67, v66
	s_nop 1
	v_permlane16_swap_b32_e32 v67, v66
	v_pk_mul_f32 v[68:69], v[70:71], v[70:71]
	v_pk_mul_f32 v[88:89], v[74:75], v[74:75]
	v_pk_mul_f32 v[90:91], v[72:73], v[72:73]
	v_pk_mul_f32 v[92:93], v[76:77], v[76:77]
	s_waitcnt lgkmcnt(0)
	v_add_f32_e32 v66, v66, v67
	s_mov_b64 s[42:43], -1
	v_mov_b32_e32 v67, v66
	v_mov_b32_e32 v252, v66
	s_nop 1
	v_permlane32_swap_b32_e32 v67, v252
	s_and_b64 vcc, exec, s[10:11]
	s_waitcnt lgkmcnt(0)
	v_add_f32_e32 v67, v67, v252
	v_add_f32_e32 v66, v69, v68
	v_add_f32_e32 v66, v88, v66
	v_add_f32_e32 v66, v89, v66
	v_add_f32_e32 v66, v90, v66
	v_add_f32_e32 v66, v91, v66
	v_add_f32_e32 v66, v92, v66
	v_add_f32_e32 v66, v93, v66
	v_mov_b32_e32 v68, v66
	s_nop 1
	v_permlane16_swap_b32_e32 v68, v66
	s_waitcnt lgkmcnt(0)
	v_add_f32_e32 v66, v66, v68
	s_nop 0
	v_mov_b32_e32 v68, v66
	v_mov_b32_e32 v252, v66
	s_nop 1
	v_permlane32_swap_b32_e32 v68, v252
	s_waitcnt lgkmcnt(0)
	v_add_f32_e32 v69, v68, v252
	s_cbranch_vccnz .LBB0_1019
	v_add_f32_e32 v66, v67, v69
	v_fmamk_f32 v66, v66, 0x3c800000, v228
	v_rsq_f32_e32 v66, v66
	s_mov_b64 s[42:43], 0

.LBB0_1043:
	v_pk_mul_f32 v[50:51], v[62:63], v[62:63]
	v_pk_mul_f32 v[52:53], v[68:69], v[68:69]
	v_add_f32_e32 v50, v51, v50
	v_add_f32_e32 v50, v52, v50
	v_pk_mul_f32 v[72:73], v[64:65], v[64:65]
	v_add_f32_e32 v50, v53, v50
	v_add_f32_e32 v50, v72, v50
	v_pk_mul_f32 v[74:75], v[70:71], v[70:71]
	v_add_f32_e32 v50, v73, v50
	v_add_f32_e32 v50, v74, v50
	v_add_f32_e32 v50, v75, v50
	v_mov_b32_e32 v51, v50
	s_nop 1
	v_permlane16_swap_b32_e32 v51, v50
	v_pk_mul_f32 v[52:53], v[54:55], v[54:55]
	v_pk_mul_f32 v[72:73], v[58:59], v[58:59]
	v_pk_mul_f32 v[74:75], v[56:57], v[56:57]
	v_pk_mul_f32 v[76:77], v[60:61], v[60:61]
	s_waitcnt lgkmcnt(0)
	v_add_f32_e32 v50, v50, v51
	s_mov_b64 s[42:43], -1
	v_mov_b32_e32 v51, v50
	v_mov_b32_e32 v252, v50
	s_nop 1
	v_permlane32_swap_b32_e32 v51, v252
	s_and_b64 vcc, exec, s[10:11]
	s_waitcnt lgkmcnt(0)
	v_add_f32_e32 v51, v51, v252
	v_add_f32_e32 v50, v53, v52
	v_add_f32_e32 v50, v72, v50
	v_add_f32_e32 v50, v73, v50
	v_add_f32_e32 v50, v74, v50
	v_add_f32_e32 v50, v75, v50
	v_add_f32_e32 v50, v76, v50
	v_add_f32_e32 v50, v77, v50
	v_mov_b32_e32 v52, v50
	s_nop 1
	v_permlane16_swap_b32_e32 v52, v50
	s_waitcnt lgkmcnt(0)
	v_add_f32_e32 v50, v50, v52
	s_nop 0
	v_mov_b32_e32 v52, v50
	v_mov_b32_e32 v252, v50
	s_nop 1
	v_permlane32_swap_b32_e32 v52, v252
	s_waitcnt lgkmcnt(0)
	v_add_f32_e32 v53, v52, v252
	s_cbranch_vccnz .LBB0_1045
	v_add_f32_e32 v50, v51, v53
	v_fmamk_f32 v50, v50, 0x3c800000, v228
	v_rsq_f32_e32 v50, v50
	s_mov_b64 s[42:43], 0

.LBB0_1069:
	v_pk_mul_f32 v[34:35], v[46:47], v[46:47]
	v_pk_mul_f32 v[36:37], v[52:53], v[52:53]
	v_add_f32_e32 v34, v35, v34
	v_add_f32_e32 v34, v36, v34
	v_pk_mul_f32 v[56:57], v[48:49], v[48:49]
	v_add_f32_e32 v34, v37, v34
	v_add_f32_e32 v34, v56, v34
	v_pk_mul_f32 v[58:59], v[54:55], v[54:55]
	v_add_f32_e32 v34, v57, v34
	v_add_f32_e32 v34, v58, v34
	v_add_f32_e32 v34, v59, v34
	v_mov_b32_e32 v35, v34
	s_nop 1
	v_permlane16_swap_b32_e32 v35, v34
	v_pk_mul_f32 v[36:37], v[38:39], v[38:39]
	v_pk_mul_f32 v[56:57], v[42:43], v[42:43]
	v_pk_mul_f32 v[58:59], v[40:41], v[40:41]
	v_pk_mul_f32 v[60:61], v[44:45], v[44:45]
	s_waitcnt lgkmcnt(0)
	v_add_f32_e32 v34, v34, v35
	s_mov_b64 s[42:43], -1
	v_mov_b32_e32 v35, v34
	v_mov_b32_e32 v252, v34
	s_nop 1
	v_permlane32_swap_b32_e32 v35, v252
	s_and_b64 vcc, exec, s[10:11]
	s_waitcnt lgkmcnt(0)
	v_add_f32_e32 v35, v35, v252
	v_add_f32_e32 v34, v37, v36
	v_add_f32_e32 v34, v56, v34
	v_add_f32_e32 v34, v57, v34
	v_add_f32_e32 v34, v58, v34
	v_add_f32_e32 v34, v59, v34
	v_add_f32_e32 v34, v60, v34
	v_add_f32_e32 v34, v61, v34
	v_mov_b32_e32 v36, v34
	s_nop 1
	v_permlane16_swap_b32_e32 v36, v34
	s_waitcnt lgkmcnt(0)
	v_add_f32_e32 v34, v34, v36
	s_nop 0
	v_mov_b32_e32 v36, v34
	v_mov_b32_e32 v252, v34
	s_nop 1
	v_permlane32_swap_b32_e32 v36, v252
	s_waitcnt lgkmcnt(0)
	v_add_f32_e32 v37, v36, v252
	s_cbranch_vccnz .LBB0_1071
	v_add_f32_e32 v34, v35, v37
	v_fmamk_f32 v34, v34, 0x3c800000, v228
	v_rsq_f32_e32 v34, v34
	s_mov_b64 s[42:43], 0

.LBB0_1095:
	v_pk_mul_f32 v[18:19], v[30:31], v[30:31]
	v_pk_mul_f32 v[20:21], v[36:37], v[36:37]
	v_add_f32_e32 v18, v19, v18
	v_add_f32_e32 v18, v20, v18
	v_pk_mul_f32 v[40:41], v[32:33], v[32:33]
	v_add_f32_e32 v18, v21, v18
	v_add_f32_e32 v18, v40, v18
	v_pk_mul_f32 v[42:43], v[38:39], v[38:39]
	v_add_f32_e32 v18, v41, v18
	v_add_f32_e32 v18, v42, v18
	v_add_f32_e32 v18, v43, v18
	v_mov_b32_e32 v19, v18
	s_nop 1
	v_permlane16_swap_b32_e32 v19, v18
	v_pk_mul_f32 v[20:21], v[22:23], v[22:23]
	v_pk_mul_f32 v[40:41], v[26:27], v[26:27]
	v_pk_mul_f32 v[42:43], v[24:25], v[24:25]
	v_pk_mul_f32 v[44:45], v[28:29], v[28:29]
	s_waitcnt lgkmcnt(0)
	v_add_f32_e32 v18, v18, v19
	s_mov_b64 s[42:43], -1
	v_mov_b32_e32 v19, v18
	v_mov_b32_e32 v252, v18
	s_nop 1
	v_permlane32_swap_b32_e32 v19, v252
	s_and_b64 vcc, exec, s[10:11]
	s_waitcnt lgkmcnt(0)
	v_add_f32_e32 v19, v19, v252
	v_add_f32_e32 v18, v21, v20
	v_add_f32_e32 v18, v40, v18
	v_add_f32_e32 v18, v41, v18
	v_add_f32_e32 v18, v42, v18
	v_add_f32_e32 v18, v43, v18
	v_add_f32_e32 v18, v44, v18
	v_add_f32_e32 v18, v45, v18
	v_mov_b32_e32 v20, v18
	s_nop 1
	v_permlane16_swap_b32_e32 v20, v18
	s_waitcnt lgkmcnt(0)
	v_add_f32_e32 v18, v18, v20
	s_nop 0
	v_mov_b32_e32 v20, v18
	v_mov_b32_e32 v252, v18
	s_nop 1
	v_permlane32_swap_b32_e32 v20, v252
	s_waitcnt lgkmcnt(0)
	v_add_f32_e32 v21, v20, v252
	s_cbranch_vccnz .LBB0_1097
	v_add_f32_e32 v18, v19, v21
	v_fmamk_f32 v18, v18, 0x3c800000, v228
	v_rsq_f32_e32 v18, v18
	s_mov_b64 s[42:43], 0

.LBB0_1121:
	v_pk_mul_f32 v[2:3], v[14:15], v[14:15]
	v_pk_mul_f32 v[4:5], v[20:21], v[20:21]
	v_add_f32_e32 v2, v3, v2
	v_add_f32_e32 v2, v4, v2
	v_pk_mul_f32 v[24:25], v[16:17], v[16:17]
	v_add_f32_e32 v2, v5, v2
	v_add_f32_e32 v2, v24, v2
	v_pk_mul_f32 v[26:27], v[22:23], v[22:23]
	v_add_f32_e32 v2, v25, v2
	v_add_f32_e32 v2, v26, v2
	v_add_f32_e32 v2, v27, v2
	v_mov_b32_e32 v3, v2
	v_mov_b32_e32 v252, v2
	s_nop 1
	v_permlane16_swap_b32_e32 v3, v252
	v_pk_mul_f32 v[4:5], v[10:11], v[10:11]
	v_pk_mul_f32 v[24:25], v[8:9], v[8:9]
	v_pk_mul_f32 v[26:27], v[12:13], v[12:13]
	s_and_b64 vcc, exec, s[10:11]
	s_waitcnt lgkmcnt(0)
	v_add_f32_e32 v28, v3, v252
	v_mov_b32_e32 v2, v1
	s_mov_b64 s[6:7], -1
	v_mbcnt_lo_u32_b32 v29, -1, v2
	v_pk_mul_f32 v[2:3], v[6:7], v[6:7]
	s_nop 0
	v_add_f32_e32 v2, v3, v2
	v_add_f32_e32 v2, v4, v2
	v_add_f32_e32 v2, v5, v2
	v_add_f32_e32 v2, v24, v2
	v_add_f32_e32 v2, v25, v2
	v_add_f32_e32 v2, v26, v2
	v_add_f32_e32 v2, v27, v2
	v_mov_b32_e32 v3, v2
	s_nop 1
	v_permlane16_swap_b32_e32 v3, v2
	v_mbcnt_hi_u32_b32 v4, -1, v29
	v_lshlrev_b32_e32 v4, 2, v4
	v_xor_b32_e32 v4, 0x80, v4
	ds_bpermute_b32 v4, v4, v28
	s_waitcnt lgkmcnt(1)
	v_add_f32_e32 v2, v2, v3
	s_waitcnt lgkmcnt(0)
	v_add_f32_e32 v5, v28, v4
	v_mov_b32_e32 v3, v2
	v_mov_b32_e32 v252, v2
	s_nop 1
	v_permlane32_swap_b32_e32 v3, v252
	s_waitcnt lgkmcnt(0)
	v_add_f32_e32 v3, v3, v252
	s_cbranch_vccnz .LBB0_1123
	v_add_f32_e32 v2, v5, v3
	v_fmamk_f32 v2, v2, 0x3c800000, v228
	v_rsq_f32_e32 v2, v2
	s_mov_b64 s[6:7], 0
